# convT tile loop: conv weights loaded on the first tile only; the next tile's row prefetch is no longer waited for right after issue (waited before the tile's stores)
# speedup vs baseline: 1.0042x; 1.0021x over previous
.LBB0_526:
	s_add_u32 s0, s78, 0xca00000
	s_addc_u32 s1, s79, 0
	s_andn2_b64 vcc, exec, s[2:3]
	s_cbranch_vccnz .LBB0_557
	s_movk_i32 s2, 0x630
	v_cmp_gt_i32_e64 s[4:5], s2, v17
	s_mov_b32 s2, 0x3e0f83e1
	v_mul_hi_i32 v18, v17, s2
	v_lshrrev_b32_e32 v19, 31, v18
	v_ashrrev_i32_e32 v18, 7, v18
	v_add_u32_e32 v20, v18, v19
	v_mul_i32_i24_e32 v18, 0x210, v20
	v_sub_u32_e32 v18, v17, v18
	v_ashrrev_i32_e32 v37, 3, v18
	v_lshlrev_b32_e32 v18, 10, v20
	v_ashrrev_i32_e32 v19, 31, v18
	v_lshl_add_u64 v[38:39], v[18:19], 1, s[84:85]
	v_add_u32_e32 v18, 0x200, v17
	v_mul_hi_i32 v19, v18, s2
	v_lshrrev_b32_e32 v21, 31, v19
	v_ashrrev_i32_e32 v19, 7, v19
	v_add_u32_e32 v21, v19, v21
	v_mul_i32_i24_e32 v19, 0x210, v21
	v_sub_u32_e32 v18, v18, v19
	v_ashrrev_i32_e32 v47, 3, v18
	v_lshlrev_b32_e32 v18, 10, v21
	v_ashrrev_i32_e32 v19, 31, v18
	v_lshl_add_u64 v[40:41], v[18:19], 1, s[84:85]
	v_add_u32_e32 v18, 0x400, v17
	v_mul_hi_i32 v19, v18, s2
	v_lshrrev_b32_e32 v22, 31, v19
	v_ashrrev_i32_e32 v19, 7, v19
	v_add_u32_e32 v22, v19, v22
	v_mul_i32_i24_e32 v19, 0x210, v22
	v_sub_u32_e32 v18, v18, v19
	v_ashrrev_i32_e32 v49, 3, v18
	v_lshlrev_b32_e32 v18, 10, v22
	v_ashrrev_i32_e32 v19, 31, v18
	v_lshl_add_u64 v[42:43], v[18:19], 1, s[84:85]
	v_add_u32_e32 v18, 0x600, v17
	v_mul_hi_i32 v19, v18, s2
	v_lshrrev_b32_e32 v23, 31, v19
	v_ashrrev_i32_e32 v19, 7, v19
	v_add_u32_e32 v23, v19, v23
	v_mul_i32_i24_e32 v19, 0x210, v23
	v_sub_u32_e32 v18, v18, v19
	v_ashrrev_i32_e32 v51, 3, v18
	v_lshlrev_b32_e32 v18, 10, v23
	v_ashrrev_i32_e32 v19, 31, v18
	s_movk_i32 s3, 0x430
	v_lshl_add_u64 v[44:45], v[18:19], 1, s[84:85]
	v_mul_i32_i24_e32 v18, 0x42, v20
	v_cmp_gt_i32_e64 s[6:7], s3, v17
	s_movk_i32 s3, 0x230
	v_add_lshl_u32 v20, v18, v37, 7
	v_mul_i32_i24_e32 v18, 0x42, v21
	v_cmp_gt_i32_e64 s[8:9], s3, v17
	v_cmp_gt_i32_e64 s[10:11], 48, v17
	v_add_lshl_u32 v21, v18, v47, 7
	v_mul_i32_i24_e32 v18, 0x42, v22
	v_and_b32_e32 v46, 63, v17
	v_ashrrev_i32_e32 v17, 3, v17
	v_add_lshl_u32 v22, v18, v49, 7
	v_mul_i32_i24_e32 v18, 0x42, v23
	v_and_b32_e32 v53, -8, v17
	s_movk_i32 s2, 0x41
	v_add_lshl_u32 v23, v18, v51, 7
	v_mad_u32_u24 v18, v46, s2, v53
	v_lshl_add_u32 v59, v18, 2, 0
	v_mov_b32_e32 v18, 0x380
	v_or_b32_e32 v69, 7, v17
	v_lshl_or_b32 v29, v17, 7, v18
	v_mad_u32_u24 v18, v46, s2, v69
	v_lshl_add_u32 v70, v18, 2, 0
	v_mad_u64_u32 v[18:19], s[14:15], v53, s2, v[46:47]
	v_and_b32_e32 v36, 56, v16
	v_or_b32_e32 v55, 1, v53
	v_or_b32_e32 v57, 2, v53
	v_lshl_add_u32 v71, v18, 2, 0
	v_mad_u64_u32 v[18:19], s[14:15], v69, s2, v[46:47]
	v_lshl_add_u32 v24, v36, 1, 0
	v_lshl_add_u32 v25, v46, 1, 0
	v_lshlrev_b32_e32 v26, 7, v53
	v_lshlrev_b32_e32 v27, 7, v55
	v_lshlrev_b32_e32 v28, 7, v57
	v_lshlrev_b32_e32 v17, 7, v69
	v_readlane_b32 s14, v253, 3
	v_mov_b32_e32 v16, 0
	s_mov_b32 s3, 0
	v_or_b32_e32 v61, 3, v53
	v_or_b32_e32 v63, 4, v53
	v_or_b32_e32 v65, 5, v53
	v_or_b32_e32 v67, 6, v53
	v_lshl_add_u32 v72, v18, 2, 0
	s_lshl_b32 s22, s14, 2
	s_lshl_b32 s23, s14, 6
	s_movk_i32 s24, 0x2000
	s_movk_i32 s25, 0xc00
	v_add_u32_e32 v73, v24, v20
	v_add_u32_e32 v74, v24, v21
	v_add_u32_e32 v75, v24, v22
	v_add_u32_e32 v76, v24, v23
	v_add_u32_e32 v77, v25, v26
	v_add_u32_e32 v78, v25, v27
	v_add_u32_e32 v79, v25, v28
	v_add_u32_e32 v80, v25, v29
	v_add_u32_e32 v81, v25, v17
	s_movk_i32 s33, 0x7fff
	s_mov_b32 s35, s95
	v_readlane_b32 s15, v253, 4
	s_mov_b32 s98, 0
	s_branch .LBB0_529

.LBB0_534:
	s_cmp_eq_u32 s98, 0
	s_cbranch_scc0 .Lmy_cvw_0
	s_waitcnt vmcnt(0)
.Lmy_cvw_0:
	ds_write_b128 v76, v[8:11] offset:33280
.LBB0_535:
	s_or_b64 exec, exec, s[28:29]
	s_and_b32 s2, s21, 0x3c0
	v_readlane_b32 s52, v253, 7
	v_or_b32_e32 v17, s2, v46
	v_readlane_b32 s66, v253, 21
	v_readlane_b32 s67, v253, 22
	v_lshlrev_b32_e32 v82, 2, v17
	v_mov_b32_e32 v83, v16
	s_mov_b64 s[30:31], s[66:67]
	v_lshl_add_u64 v[84:85], s[30:31], 0, v[82:83]
	s_and_b32 s28, s20, 0xffffffc0
	s_cmp_eq_u32 s98, 0
	s_cbranch_scc0 .Lmy_cw_cached
	v_add_co_u32_e32 v86, vcc, 0x3000, v84
	global_load_dword v247, v82, s[48:49]
	global_load_dword v68, v82, s[66:67]
	v_addc_co_u32_e32 v87, vcc, 0, v85, vcc
	global_load_dword v66, v[86:87], off
	v_add_co_u32_e32 v86, vcc, 0x6000, v84
	v_or_b32_e32 v17, 0x1000, v82
	s_nop 0
	v_addc_co_u32_e32 v87, vcc, 0, v85, vcc
	global_load_dword v64, v[86:87], off
	v_add_co_u32_e32 v86, vcc, 0x4000, v84
	global_load_dword v248, v17, s[48:49]
	global_load_dword v62, v17, s[66:67]
	v_addc_co_u32_e32 v87, vcc, 0, v85, vcc
	global_load_dword v60, v[86:87], off
	v_add_co_u32_e32 v86, vcc, 0x7000, v84
	v_or_b32_e32 v17, 0x2000, v82
	s_nop 0
	v_addc_co_u32_e32 v87, vcc, 0, v85, vcc
	v_add_co_u32_e32 v82, vcc, 0x5000, v84
	global_load_dword v58, v[86:87], off
	s_nop 0
	v_addc_co_u32_e32 v83, vcc, 0, v85, vcc
	global_load_dword v249, v17, s[48:49]
	global_load_dword v56, v17, s[66:67]
	global_load_dword v54, v[82:83], off
	v_add_co_u32_e32 v82, vcc, 0x8000, v84
	s_nop 0
	v_addc_co_u32_e32 v83, vcc, 0, v85, vcc
	global_load_dword v52, v[82:83], off
	s_mov_b32 s98, 1
	s_waitcnt vmcnt(0)
.Lmy_cw_cached:
	v_mov_b32_e32 v18, v247
	v_mov_b32_e32 v48, v248
	v_mov_b32_e32 v50, v249
	s_waitcnt lgkmcnt(0)
	s_barrier
	ds_read_u16 v17, v77 offset:41728
	ds_read_u16 v19, v77 offset:41856
	s_ashr_i32 s29, s28, 31
	s_andn2_b64 vcc, exec, s[26:27]
	v_readlane_b32 s53, v253, 8
	s_waitcnt lgkmcnt(1)
	v_lshlrev_b32_e32 v82, 16, v17
	ds_read_u16 v17, v77 offset:42112
	ds_read_u16 v83, v77 offset:41984
	v_readlane_b32 s54, v253, 9
	v_readlane_b32 s55, v253, 10
	v_readlane_b32 s56, v253, 11
	s_waitcnt lgkmcnt(1)
	v_lshlrev_b32_e32 v85, 16, v17
	s_waitcnt lgkmcnt(0)
	v_lshlrev_b32_e32 v84, 16, v83
	v_lshlrev_b32_e32 v83, 16, v19
	ds_read_u16 v17, v77 offset:50176
	ds_read_u16 v19, v77 offset:50304
	v_mov_b32_e32 v86, v83
	v_mov_b32_e32 v87, v84
	v_readlane_b32 s57, v253, 12
	s_waitcnt lgkmcnt(1)
	v_lshlrev_b32_e32 v88, 16, v17
	ds_read_u16 v17, v77 offset:50560
	ds_read_u16 v89, v77 offset:50432
	v_readlane_b32 s58, v253, 13
	v_readlane_b32 s59, v253, 14
	v_readlane_b32 s60, v253, 15
	s_waitcnt lgkmcnt(1)
	v_lshlrev_b32_e32 v91, 16, v17
	s_waitcnt lgkmcnt(0)
	v_lshlrev_b32_e32 v90, 16, v89
	v_lshlrev_b32_e32 v89, 16, v19
	v_mov_b32_e32 v92, v89
	v_mov_b32_e32 v93, v90
	v_readlane_b32 s61, v253, 16
	v_readlane_b32 s62, v253, 17
	v_readlane_b32 s63, v253, 18
	v_readlane_b32 s64, v253, 19
	v_readlane_b32 s65, v253, 20
	v_pk_fma_f32 v[82:83], v[62:63], v[82:83], v[48:49] op_sel_hi:[0,1,0]
	v_pk_fma_f32 v[82:83], v[60:61], v[86:87], v[82:83] op_sel_hi:[0,1,1]
	v_pk_fma_f32 v[82:83], v[58:59], v[84:85], v[82:83] op_sel_hi:[0,1,1]
	v_pk_fma_f32 v[86:87], v[56:57], v[88:89], v[50:51] op_sel_hi:[0,1,0]
	v_pk_fma_f32 v[86:87], v[54:55], v[92:93], v[86:87] op_sel_hi:[0,1,1]
	v_pk_fma_f32 v[86:87], v[52:53], v[90:91], v[86:87] op_sel_hi:[0,1,1]
	v_pk_mul_f32 v[82:83], v[82:83], v[86:87]
	ds_write2_b32 v59, v82, v83 offset1:1
	ds_read_u16 v17, v77 offset:33280
	ds_read_u16 v19, v78 offset:33280
	s_waitcnt lgkmcnt(1)
	v_lshlrev_b32_e32 v82, 16, v17
	ds_read_u16 v17, v77 offset:33664
	ds_read_u16 v83, v79 offset:33280
	s_waitcnt lgkmcnt(1)
	v_lshlrev_b32_e32 v87, 16, v17
	s_waitcnt lgkmcnt(0)
	v_lshlrev_b32_e32 v86, 16, v83
	v_lshlrev_b32_e32 v83, 16, v19
	v_mov_b32_e32 v88, v83
	v_mov_b32_e32 v89, v86
	v_pk_fma_f32 v[82:83], v[68:69], v[82:83], v[18:19] op_sel_hi:[0,1,0]
	v_pk_fma_f32 v[82:83], v[66:67], v[88:89], v[82:83] op_sel_hi:[0,1,1]
	v_pk_fma_f32 v[82:83], v[64:65], v[86:87], v[82:83] op_sel_hi:[0,1,1]
	v_add_u32_e32 v17, 0x4100, v59
	ds_write2_b32 v17, v82, v83 offset1:1
	ds_read_u16 v17, v77 offset:42240
	ds_read_u16 v19, v77 offset:42368
	v_pk_fma_f32 v[82:83], v[62:63], v[84:85], v[48:49] op_sel_hi:[0,1,0]
	s_waitcnt lgkmcnt(1)
	v_lshlrev_b32_e32 v88, 16, v17
	s_waitcnt lgkmcnt(0)
	v_lshlrev_b32_e32 v89, 16, v19
	ds_read_u16 v17, v77 offset:50688
	ds_read_u16 v19, v77 offset:50816
	v_pk_mov_b32 v[84:85], v[84:85], v[88:89] op_sel:[1,0]
	s_waitcnt lgkmcnt(1)
	v_lshlrev_b32_e32 v92, 16, v17
	s_waitcnt lgkmcnt(0)
	v_lshlrev_b32_e32 v93, 16, v19
	ds_read_u16 v17, v77 offset:33792
	ds_read_u16 v19, v77 offset:33920
	v_pk_fma_f32 v[82:83], v[60:61], v[84:85], v[82:83] op_sel_hi:[0,1,1]
	v_pk_fma_f32 v[84:85], v[56:57], v[90:91], v[50:51] op_sel_hi:[0,1,0]
	v_pk_mov_b32 v[90:91], v[90:91], v[92:93] op_sel:[1,0]
	v_pk_fma_f32 v[82:83], v[58:59], v[88:89], v[82:83] op_sel_hi:[0,1,1]
	v_pk_fma_f32 v[84:85], v[54:55], v[90:91], v[84:85] op_sel_hi:[0,1,1]
	v_pk_fma_f32 v[84:85], v[52:53], v[92:93], v[84:85] op_sel_hi:[0,1,1]
	v_pk_mul_f32 v[82:83], v[82:83], v[84:85]
	s_waitcnt lgkmcnt(0)
	v_lshlrev_b32_e32 v85, 16, v19
	v_lshlrev_b32_e32 v84, 16, v17
	ds_write2_b32 v59, v82, v83 offset0:2 offset1:3
	v_pk_fma_f32 v[82:83], v[68:69], v[86:87], v[18:19] op_sel_hi:[0,1,0]
	v_pk_mov_b32 v[86:87], v[86:87], v[84:85] op_sel:[1,0]
	v_add_u32_e32 v17, 0x4108, v59
	v_pk_fma_f32 v[82:83], v[66:67], v[86:87], v[82:83] op_sel_hi:[0,1,1]
	v_pk_fma_f32 v[82:83], v[64:65], v[84:85], v[82:83] op_sel_hi:[0,1,1]
	ds_write2_b32 v17, v82, v83 offset1:1
	ds_read_u16 v17, v77 offset:42624
	ds_read_u16 v19, v77 offset:42496
	v_pk_fma_f32 v[82:83], v[62:63], v[88:89], v[48:49] op_sel_hi:[0,1,0]
	s_waitcnt lgkmcnt(1)
	v_lshlrev_b32_e32 v87, 16, v17
	s_waitcnt lgkmcnt(0)
	v_lshlrev_b32_e32 v86, 16, v19
	ds_read_u16 v17, v77 offset:51072
	ds_read_u16 v19, v77 offset:50944
	v_pk_mov_b32 v[88:89], v[88:89], v[86:87] op_sel:[1,0]
	s_waitcnt lgkmcnt(1)
	v_lshlrev_b32_e32 v91, 16, v17
	s_waitcnt lgkmcnt(0)
	v_lshlrev_b32_e32 v90, 16, v19
	v_pk_fma_f32 v[82:83], v[60:61], v[88:89], v[82:83] op_sel_hi:[0,1,1]
	v_pk_fma_f32 v[88:89], v[56:57], v[92:93], v[50:51] op_sel_hi:[0,1,0]
	v_pk_mov_b32 v[92:93], v[92:93], v[90:91] op_sel:[1,0]
	v_pk_fma_f32 v[82:83], v[58:59], v[86:87], v[82:83] op_sel_hi:[0,1,1]
	v_pk_fma_f32 v[88:89], v[54:55], v[92:93], v[88:89] op_sel_hi:[0,1,1]
	v_pk_fma_f32 v[88:89], v[52:53], v[90:91], v[88:89] op_sel_hi:[0,1,1]
	v_pk_mul_f32 v[82:83], v[82:83], v[88:89]
	ds_write2_b32 v59, v82, v83 offset0:4 offset1:5
	v_pk_fma_f32 v[82:83], v[68:69], v[84:85], v[18:19] op_sel_hi:[0,1,0]
	ds_read_u16 v17, v80 offset:33280
	ds_read_u16 v19, v77 offset:34048
	s_waitcnt lgkmcnt(1)
	v_lshlrev_b32_e32 v89, 16, v17
	s_waitcnt lgkmcnt(0)
	v_lshlrev_b32_e32 v88, 16, v19
	v_pk_mov_b32 v[84:85], v[84:85], v[88:89] op_sel:[1,0]
	ds_read_u16 v19, v77 offset:34304
	v_pk_fma_f32 v[82:83], v[66:67], v[84:85], v[82:83] op_sel_hi:[0,1,1]
	v_pk_fma_f32 v[82:83], v[64:65], v[88:89], v[82:83] op_sel_hi:[0,1,1]
	v_add_u32_e32 v17, 0x4110, v59
	ds_write2_b32 v17, v82, v83 offset1:1
	ds_read_u16 v82, v77 offset:42752
	ds_read_u16 v83, v77 offset:51200
	v_fma_f32 v17, v68, v88, v18
	v_fmac_f32_e32 v17, v66, v89
	s_waitcnt lgkmcnt(3)
	v_lshlrev_b32_e32 v19, 16, v19
	v_fmac_f32_e32 v17, v64, v19
	v_fma_f32 v19, v62, v86, v48
	v_fmac_f32_e32 v19, v60, v87
	s_waitcnt lgkmcnt(1)
	v_lshlrev_b32_e32 v82, 16, v82
	v_fmac_f32_e32 v19, v58, v82
	v_fma_f32 v82, v56, v90, v50
	v_fmac_f32_e32 v82, v54, v91
	s_waitcnt lgkmcnt(0)
	v_lshlrev_b32_e32 v83, 16, v83
	v_fmac_f32_e32 v82, v52, v83
	v_mul_f32_e32 v19, v19, v82
	v_add_u32_e32 v82, 24, v59
	ds_write2st64_b32 v82, v19, v17 offset1:65
	ds_read_u16 v17, v81 offset:33280
	v_add_u32_e32 v84, s2, v53
	v_ashrrev_i32_e32 v85, 31, v84
	v_mov_b32_e32 v19, s29
	v_lshlrev_b64 v[84:85], 13, v[84:85]
	s_waitcnt lgkmcnt(0)
	v_lshlrev_b32_e32 v17, 16, v17
	v_fmac_f32_e32 v18, v68, v17
	ds_read_u16 v17, v81 offset:33408
	s_waitcnt lgkmcnt(0)
	v_lshlrev_b32_e32 v17, 16, v17
	v_fmac_f32_e32 v18, v66, v17
	ds_read_u16 v17, v81 offset:33536
	s_waitcnt lgkmcnt(0)
	v_lshlrev_b32_e32 v17, 16, v17
	v_fmac_f32_e32 v18, v64, v17
	ds_read_u16 v17, v81 offset:41728
	s_waitcnt lgkmcnt(0)
	v_lshlrev_b32_e32 v17, 16, v17
	v_fmac_f32_e32 v48, v62, v17
	ds_read_u16 v17, v81 offset:41856
	s_waitcnt lgkmcnt(0)
	v_lshlrev_b32_e32 v17, 16, v17
	v_fmac_f32_e32 v48, v60, v17
	ds_read_u16 v17, v81 offset:41984
	s_waitcnt lgkmcnt(0)
	v_lshlrev_b32_e32 v17, 16, v17
	v_fmac_f32_e32 v48, v58, v17
	ds_read_u16 v17, v81 offset:50176
	s_waitcnt lgkmcnt(0)
	v_lshlrev_b32_e32 v17, 16, v17
	v_fmac_f32_e32 v50, v56, v17
	ds_read_u16 v17, v81 offset:50304
	s_waitcnt lgkmcnt(0)
	v_lshlrev_b32_e32 v17, 16, v17
	v_fmac_f32_e32 v50, v54, v17
	ds_read_u16 v17, v81 offset:50432
	s_waitcnt lgkmcnt(0)
	v_lshlrev_b32_e32 v17, 16, v17
	v_fmac_f32_e32 v50, v52, v17
	v_mul_f32_e32 v17, v48, v50
	ds_write2st64_b32 v70, v17, v18 offset1:65
	s_waitcnt lgkmcnt(0)
	s_barrier
	ds_read2_b32 v[82:83], v71 offset1:65
	v_or_b32_e32 v18, s28, v46
	v_lshl_add_u64 v[84:85], v[84:85], 0, v[18:19]
	v_lshlrev_b64 v[84:85], 1, v[84:85]
	v_lshl_add_u64 v[86:87], s[16:17], 0, v[84:85]
	s_waitcnt lgkmcnt(0)
	v_bfe_u32 v17, v82, 16, 1
	v_add3_u32 v17, v82, v17, s33
	s_waitcnt vmcnt(0)
	global_store_short_d16_hi v[86:87], v17, off
	v_add_u32_e32 v17, 0x4000, v71
	ds_read2_b32 v[86:87], v17 offset0:64 offset1:129
	v_lshl_add_u64 v[84:85], s[0:1], 0, v[84:85]
	v_add_u32_e32 v82, s2, v55
	s_waitcnt lgkmcnt(0)
	v_bfe_u32 v17, v86, 16, 1
	v_add3_u32 v17, v86, v17, s33
	global_store_short_d16_hi v[84:85], v17, off
	v_bfe_u32 v17, v83, 16, 1
	v_add3_u32 v17, v83, v17, s33
	v_ashrrev_i32_e32 v83, 31, v82
	v_lshlrev_b64 v[82:83], 13, v[82:83]
	v_lshl_add_u64 v[82:83], v[82:83], 0, v[18:19]
	v_lshlrev_b64 v[82:83], 1, v[82:83]
	v_lshl_add_u64 v[84:85], s[16:17], 0, v[82:83]
	global_store_short_d16_hi v[84:85], v17, off
	v_bfe_u32 v17, v87, 16, 1
	v_add3_u32 v17, v87, v17, s33
	v_lshl_add_u64 v[82:83], s[0:1], 0, v[82:83]
	global_store_short_d16_hi v[82:83], v17, off
	ds_read2_b32 v[82:83], v71 offset0:130 offset1:195
	v_add_u32_e32 v84, s2, v57
	v_ashrrev_i32_e32 v85, 31, v84
	v_lshlrev_b64 v[84:85], 13, v[84:85]
	v_lshl_add_u64 v[84:85], v[84:85], 0, v[18:19]
	s_waitcnt lgkmcnt(0)
	v_bfe_u32 v17, v82, 16, 1
	v_lshlrev_b64 v[84:85], 1, v[84:85]
	v_add3_u32 v17, v82, v17, s33
	v_lshl_add_u64 v[86:87], s[16:17], 0, v[84:85]
	global_store_short_d16_hi v[86:87], v17, off
	v_add_u32_e32 v17, 0x4200, v71
	ds_read2_b32 v[86:87], v17 offset0:66 offset1:131
	v_lshl_add_u64 v[84:85], s[0:1], 0, v[84:85]
	v_add_u32_e32 v82, s2, v61
	s_waitcnt lgkmcnt(0)
	v_bfe_u32 v17, v86, 16, 1
	v_add3_u32 v17, v86, v17, s33
	global_store_short_d16_hi v[84:85], v17, off
	v_bfe_u32 v17, v83, 16, 1
	v_add3_u32 v17, v83, v17, s33
	v_ashrrev_i32_e32 v83, 31, v82
	v_lshlrev_b64 v[82:83], 13, v[82:83]
	v_lshl_add_u64 v[82:83], v[82:83], 0, v[18:19]
	v_lshlrev_b64 v[82:83], 1, v[82:83]
	v_lshl_add_u64 v[84:85], s[16:17], 0, v[82:83]
	global_store_short_d16_hi v[84:85], v17, off
	v_bfe_u32 v17, v87, 16, 1
	v_add3_u32 v17, v87, v17, s33
	v_lshl_add_u64 v[82:83], s[0:1], 0, v[82:83]
	global_store_short_d16_hi v[82:83], v17, off
	v_add_u32_e32 v17, 0x400, v71
	ds_read2_b32 v[82:83], v17 offset0:4 offset1:69
	v_add_u32_e32 v84, s2, v63
	v_ashrrev_i32_e32 v85, 31, v84
	v_lshlrev_b64 v[84:85], 13, v[84:85]
	v_lshl_add_u64 v[84:85], v[84:85], 0, v[18:19]
	s_waitcnt lgkmcnt(0)
	v_bfe_u32 v17, v82, 16, 1
	v_lshlrev_b64 v[84:85], 1, v[84:85]
	v_add3_u32 v17, v82, v17, s33
	v_lshl_add_u64 v[86:87], s[16:17], 0, v[84:85]
	global_store_short_d16_hi v[86:87], v17, off
	v_add_u32_e32 v17, 0x4400, v71
	ds_read2_b32 v[86:87], v17 offset0:68 offset1:133
	v_lshl_add_u64 v[84:85], s[0:1], 0, v[84:85]
	v_add_u32_e32 v82, s2, v65
	s_waitcnt lgkmcnt(0)
	v_bfe_u32 v17, v86, 16, 1
	v_add3_u32 v17, v86, v17, s33
	global_store_short_d16_hi v[84:85], v17, off
	v_bfe_u32 v17, v83, 16, 1
	v_add3_u32 v17, v83, v17, s33
	v_ashrrev_i32_e32 v83, 31, v82
	v_lshlrev_b64 v[82:83], 13, v[82:83]
	v_lshl_add_u64 v[82:83], v[82:83], 0, v[18:19]
	v_lshlrev_b64 v[82:83], 1, v[82:83]
	v_lshl_add_u64 v[84:85], s[16:17], 0, v[82:83]
	global_store_short_d16_hi v[84:85], v17, off
	v_bfe_u32 v17, v87, 16, 1
	v_add3_u32 v17, v87, v17, s33
	v_lshl_add_u64 v[82:83], s[0:1], 0, v[82:83]
	global_store_short_d16_hi v[82:83], v17, off
	ds_read_b32 v17, v71 offset:1560
	v_add_u32_e32 v82, s2, v67
	v_ashrrev_i32_e32 v83, 31, v82
	v_lshlrev_b64 v[82:83], 13, v[82:83]
	v_lshl_add_u64 v[82:83], v[82:83], 0, v[18:19]
	s_waitcnt lgkmcnt(0)
	v_bfe_u32 v48, v17, 16, 1
	v_lshlrev_b64 v[82:83], 1, v[82:83]
	v_add3_u32 v17, v17, v48, s33
	v_lshl_add_u64 v[84:85], s[16:17], 0, v[82:83]
	global_store_short_d16_hi v[84:85], v17, off
	ds_read_b32 v17, v71 offset:18200
	v_lshl_add_u64 v[82:83], s[0:1], 0, v[82:83]
	v_add_u32_e32 v84, s2, v69
	v_ashrrev_i32_e32 v85, 31, v84
	v_lshlrev_b64 v[84:85], 13, v[84:85]
	s_waitcnt lgkmcnt(0)
	v_bfe_u32 v48, v17, 16, 1
	v_add3_u32 v17, v17, v48, s33
	global_store_short_d16_hi v[82:83], v17, off
	ds_read2st64_b32 v[82:83], v72 offset1:65
	v_lshl_add_u64 v[18:19], v[84:85], 0, v[18:19]
	v_lshlrev_b64 v[18:19], 1, v[18:19]
	v_lshl_add_u64 v[84:85], s[16:17], 0, v[18:19]
	v_lshl_add_u64 v[18:19], s[0:1], 0, v[18:19]
	s_waitcnt lgkmcnt(0)
	v_bfe_u32 v17, v82, 16, 1
	v_add3_u32 v17, v82, v17, s33
	global_store_short_d16_hi v[84:85], v17, off
	v_bfe_u32 v17, v83, 16, 1
	v_add3_u32 v17, v83, v17, s33
	global_store_short_d16_hi v[18:19], v17, off
	s_barrier
	s_cbranch_vccnz .LBB0_528
	v_mov_b64_e32 v[8:9], v[32:33]
	v_mov_b64_e32 v[12:13], v[28:29]
	v_mov_b64_e32 v[0:1], v[20:21]
	v_mov_b64_e32 v[4:5], v[24:25]
	v_mov_b64_e32 v[10:11], v[34:35]
	v_mov_b64_e32 v[14:15], v[30:31]
	v_mov_b64_e32 v[2:3], v[22:23]
	v_mov_b64_e32 v[6:7], v[26:27]
	s_branch .LBB0_528

.Lmy_cvw_1:
	ds_write_b128 v73, v[4:7] offset:33280
	s_or_b64 exec, exec, s[28:29]
	s_and_saveexec_b64 s[28:29], s[6:7]
	s_cbranch_execz .LBB0_532

.Lmy_cvw_2:
	ds_write_b128 v74, v[0:3] offset:33280
	s_or_b64 exec, exec, s[28:29]
	s_and_saveexec_b64 s[28:29], s[8:9]
	s_cbranch_execz .LBB0_533

.Lmy_cvw_3:
	ds_write_b128 v75, v[12:15] offset:33280
	s_or_b64 exec, exec, s[28:29]
	s_and_saveexec_b64 s[28:29], s[10:11]
	s_cbranch_execnz .LBB0_534
	s_branch .LBB0_535
